# cs2: P0 also writes rotary cos/sin table in lane-coalesced layout; G1 rotary epilogue reads it (1KiB-contiguous dwordx4 loads)
# speedup vs baseline: 1.1182x; 1.0009x over previous
.LBB0_211:
	v_and_b32_e32 v12, 0xfffffe00, v3
	v_lshlrev_b32_e32 v12, 3, v12
	v_bfe_u32 v13, v3, 1, 2
	v_lshl_or_b32 v12, v13, 10, v12
	v_bfe_u32 v13, v3, 5, 4
	v_lshl_or_b32 v12, v13, 6, v12
	v_bfe_u32 v13, v3, 3, 2
	v_lshl_or_b32 v12, v13, 4, v12
	v_and_b32_e32 v13, 1, v3
	v_lshl_or_b32 v12, v13, 3, v12
	v_add_u32_e32 v12, 0xe600000, v12
	v_ashrrev_i32_e32 v7, 5, v3
	v_cvt_f32_i32_e32 v7, v7
	v_add_u32_e32 v3, s0, v3
	v_cmp_lt_i32_e32 vcc, s1, v3
	s_or_b64 s[10:11], vcc, s[10:11]
	v_mul_f32_e32 v7, v6, v7
	v_cvt_f64_f32_e32 v[8:9], v7
	v_mul_f64 v[10:11], v[8:9], s[12:13]
	v_floor_f64_e32 v[10:11], v[10:11]
	v_fma_f64 v[8:9], v[8:9], s[12:13], -v[10:11]
	v_cvt_f32_f64_e32 v7, v[8:9]
	v_cos_f32_e32 v8, v7
	v_sin_f32_e32 v9, v7
	global_store_dwordx2 v[4:5], v[8:9], off
	global_store_dwordx2 v12, v[8:9], s[74:75]
	v_lshl_add_u64 v[4:5], v[4:5], 0, s[8:9]
	s_andn2_b64 exec, exec, s[10:11]
	s_cbranch_execnz .LBB0_211

.LBB0_301:
	v_lshlrev_b32_e32 v136, 5, v148
	v_and_b32_e32 v136, 0x3f9e0, v136
	v_and_b32_e32 v150, 0x1e0, v136
	v_or_b32_e32 v150, v150, v138
	v_and_b32_e32 v136, 0xfffffe1f, v136
	v_lshlrev_b32_e32 v150, 1, v150
	v_lshl_add_u32 v136, v136, 3, v150
	v_add_u32_e32 v136, 0xe500000, v136
	v_lshl_add_u64 v[150:151], v[136:137], 0, s[6:7]
	v_ashrrev_i32_e32 v149, 31, v148
	global_load_dwordx4 v[164:167], v[150:151], off
	global_load_dwordx4 v[168:171], v[150:151], off offset:1024
	global_load_dwordx4 v[172:175], v[150:151], off offset:2048
	global_load_dwordx4 v[176:179], v[150:151], off offset:3072
	v_lshl_add_u64 v[152:153], v[148:149], 2, s[4:5]
	global_load_dword v180, v[152:153], off
	s_cmp_gt_i32 s49, 1
	v_mov_b32_e32 v191, v112
	v_mov_b32_e32 v192, v112
	v_mov_b32_e32 v112, v117
	s_cselect_b64 vcc, -1, 0
	v_mov_b32_e32 v182, v124
	v_mov_b32_e32 v183, v120
	v_mov_b32_e32 v184, v120
	v_mov_b32_e32 v185, v124
	v_mov_b32_e32 v190, v116
	v_mov_b32_e32 v193, v116
	v_mov_b32_e32 v116, v113
	v_mov_b32_e32 v151, v118
	v_mov_b32_e32 v195, v118
	v_mov_b32_e32 v118, v115
	v_cndmask_b32_e32 v150, 1.0, v163, vcc
	v_mov_b32_e32 v120, v125
	v_mov_b32_e32 v124, v121
	v_mov_b32_e32 v186, v126
	v_mov_b32_e32 v187, v122
	v_mov_b32_e32 v194, v114
	v_readlane_b32 s10, v254, 45
	v_readlane_b32 s11, v254, 46
	v_mov_b32_e32 v188, v122
	v_mov_b32_e32 v189, v126
	v_mov_b64_e32 v[154:155], s[10:11]
	s_lshl_b32 s10, s49, 8
	s_ashr_i32 s11, s10, 31
	v_mov_b32_e32 v122, v127
	v_mov_b32_e32 v126, v123
	s_lshl_b32 s8, s41, 1
	s_waitcnt vmcnt(0)
	v_pk_mul_f32 v[182:183], v[182:183], v[164:165]
	v_pk_mul_f32 v[164:165], v[184:185], v[164:165]
	v_pk_mul_f32 v[112:113], v[112:113], v[174:175]
	v_mov_b32_e32 v181, v176
	v_pk_mul_f32 v[116:117], v[116:117], v[174:175]
	v_pk_mul_f32 v[184:185], v[118:119], v[178:179]
	v_pk_mul_f32 v[180:181], v[150:151], v[180:181]
	v_sub_f32_e32 v112, v112, v113
	v_pk_mul_f32 v[120:121], v[120:121], v[166:167]
	v_pk_mul_f32 v[124:125], v[124:125], v[166:167]
	v_pk_mul_f32 v[166:167], v[186:187], v[168:169]
	v_add_f32_e32 v113, v117, v116
	v_add_f32_e32 v117, v185, v184
	v_mul_f32_e32 v151, v180, v112
	v_fma_f32 v112, -v114, v177, v181
	v_mov_b32_e32 v114, v119
	v_add_f32_e32 v136, v165, v164
	v_sub_f32_e32 v120, v120, v121
	v_add_f32_e32 v121, v125, v124
	v_sub_f32_e32 v124, v166, v167
	v_mul_f32_e32 v164, v180, v113
	v_mul_f32_e32 v166, v180, v117
	v_mul_f32_e32 v117, v180, v112
	v_pk_mul_f32 v[112:113], v[114:115], v[178:179]
	v_pk_mul_f32 v[122:123], v[122:123], v[170:171]
	v_sub_f32_e32 v112, v112, v113
	v_mul_f32_e32 v167, v180, v112
	v_mad_i64_i32 v[112:113], s[28:29], v148, s47, v[154:155]
	s_lshl_b64 s[28:29], s[10:11], 1
	v_pk_mul_f32 v[126:127], v[126:127], v[170:171]
	v_pk_mul_f32 v[170:171], v[190:191], v[172:173]
	v_lshl_add_u64 v[112:113], v[112:113], 0, s[28:29]
	v_pk_mul_f32 v[174:175], v[194:195], v[176:177]
	v_sub_f32_e32 v118, v182, v183
	v_sub_f32_e32 v122, v122, v123
	v_add_f32_e32 v123, v127, v126
	v_sub_f32_e32 v126, v170, v171
	v_lshl_add_u64 v[114:115], v[112:113], 0, s[8:9]
	v_lshlrev_b64 v[112:113], 1, v[138:139]
	v_pk_mul_f32 v[168:169], v[188:189], v[168:169]
	v_pk_mul_f32 v[172:173], v[192:193], v[172:173]
	v_add_f32_e32 v116, v175, v174
	v_mul_f32_e32 v149, v180, v118
	v_mul_f32_e32 v120, v180, v120
	v_mul_f32_e32 v126, v180, v126
	v_lshl_add_u64 v[118:119], v[114:115], 0, v[112:113]
	v_cvt_pk_bf16_f32 v114, v149, v120
	v_add_f32_e32 v125, v169, v168
	v_add_f32_e32 v127, v173, v172
	v_mul_f32_e32 v136, v180, v136
	v_mul_f32_e32 v121, v180, v121
	v_mul_f32_e32 v124, v180, v124
	v_mul_f32_e32 v122, v180, v122
	v_mul_f32_e32 v165, v180, v116
	v_cvt_pk_bf16_f32 v115, v124, v122
	v_cvt_pk_bf16_f32 v116, v126, v151
	v_cvt_pk_bf16_f32 v117, v117, v167
	global_store_dwordx4 v[118:119], v[114:117], off
	v_or_b32_e32 v126, 16, v148
	v_mul_f32_e32 v125, v180, v125
	v_cvt_pk_bf16_f32 v114, v136, v121
	v_mul_f32_e32 v123, v180, v123
	v_mul_f32_e32 v127, v180, v127
	v_cvt_pk_bf16_f32 v115, v125, v123
	v_cvt_pk_bf16_f32 v116, v127, v164
	v_cvt_pk_bf16_f32 v117, v165, v166
	global_store_dwordx4 v[118:119], v[114:117], off offset:64
	v_ashrrev_i32_e32 v127, 31, v126
	v_lshl_add_u64 v[168:169], v[126:127], 2, s[4:5]
	v_lshlrev_b32_e32 v114, 5, v126
	v_and_b32_e32 v136, 0x3fbe0, v114
	v_and_b32_e32 v114, 0x1e0, v136
	v_or_b32_e32 v114, v114, v138
	v_and_b32_e32 v136, 0xfffffe1f, v136
	v_lshlrev_b32_e32 v114, 1, v114
	v_lshl_add_u32 v136, v136, 3, v114
	v_add_u32_e32 v136, 0xe500000, v136
	v_lshl_add_u64 v[164:165], v[136:137], 0, s[6:7]
	global_load_dwordx4 v[114:117], v[164:165], off
	global_load_dwordx4 v[118:121], v[164:165], off offset:1024
	global_load_dwordx4 v[122:125], v[164:165], off offset:2048
	s_nop 0
	global_load_dwordx4 v[164:167], v[164:165], off offset:3072
	s_nop 0
	global_load_dword v168, v[168:169], off
	v_mov_b32_e32 v179, v96
	v_mov_b32_e32 v180, v96
	v_mov_b32_e32 v96, v101
	v_mov_b32_e32 v170, v108
	v_mov_b32_e32 v171, v104
	v_mov_b32_e32 v172, v104
	v_mov_b32_e32 v173, v108
	v_mov_b32_e32 v104, v109
	v_mov_b32_e32 v108, v105
	v_mov_b32_e32 v174, v110
	v_mov_b32_e32 v175, v106
	v_mov_b32_e32 v178, v100
	v_mov_b32_e32 v181, v100
	v_mov_b32_e32 v100, v97
	v_mov_b32_e32 v151, v102
	v_mov_b32_e32 v176, v106
	v_mov_b32_e32 v177, v110
	v_mov_b32_e32 v106, v111
	v_mov_b32_e32 v110, v107
	s_waitcnt vmcnt(4)
	v_pk_mul_f32 v[104:105], v[104:105], v[116:117]
	v_pk_mul_f32 v[108:109], v[108:109], v[116:117]
	s_waitcnt vmcnt(2)
	v_pk_mul_f32 v[96:97], v[96:97], v[124:125]
	s_waitcnt vmcnt(1)
	v_mov_b32_e32 v169, v164
	v_pk_mul_f32 v[116:117], v[174:175], v[118:119]
	v_pk_mul_f32 v[100:101], v[100:101], v[124:125]
	s_waitcnt vmcnt(0)
	v_pk_mul_f32 v[124:125], v[150:151], v[168:169]
	v_sub_f32_e32 v96, v96, v97
	v_pk_mul_f32 v[118:119], v[176:177], v[118:119]
	v_sub_f32_e32 v104, v104, v105
	v_add_f32_e32 v105, v109, v108
	v_sub_f32_e32 v108, v116, v117
	v_add_f32_e32 v97, v101, v100
	v_mul_f32_e32 v116, v124, v96
	v_fma_f32 v96, -v98, v165, v125
	v_add_f32_e32 v109, v119, v118
	v_mul_f32_e32 v117, v124, v97
	v_mul_f32_e32 v118, v124, v96
	v_mov_b32_e32 v96, v98
	v_mov_b32_e32 v97, v102
	v_pk_mul_f32 v[96:97], v[96:97], v[164:165]
	v_mov_b32_e32 v98, v103
	v_add_f32_e32 v96, v97, v96
	v_mul_f32_e32 v119, v124, v96
	v_pk_mul_f32 v[96:97], v[98:99], v[166:167]
	v_pk_mul_f32 v[106:107], v[106:107], v[120:121]
	v_pk_mul_f32 v[110:111], v[110:111], v[120:121]
	v_pk_mul_f32 v[120:121], v[178:179], v[122:123]
	v_sub_f32_e32 v96, v96, v97
	v_mov_b32_e32 v102, v99
	v_sub_f32_e32 v106, v106, v107
	v_add_f32_e32 v107, v111, v110
	v_sub_f32_e32 v110, v120, v121
	v_mul_f32_e32 v120, v124, v96
	v_pk_mul_f32 v[96:97], v[102:103], v[166:167]
	v_pk_mul_f32 v[170:171], v[170:171], v[114:115]
	v_add_f32_e32 v96, v97, v96
	v_mul_f32_e32 v102, v124, v96
	v_mad_i64_i32 v[96:97], s[10:11], v126, s47, v[154:155]
	v_pk_mul_f32 v[114:115], v[172:173], v[114:115]
	v_lshl_add_u64 v[96:97], v[96:97], 0, s[28:29]
	v_sub_f32_e32 v127, v170, v171
	v_add_f32_e32 v114, v115, v114
	v_lshl_add_u64 v[96:97], v[96:97], 0, s[8:9]
	v_pk_mul_f32 v[122:123], v[180:181], v[122:123]
	v_mul_f32_e32 v115, v124, v127
	v_mul_f32_e32 v114, v124, v114
	v_mul_f32_e32 v104, v124, v104
	v_lshl_add_u64 v[100:101], v[96:97], 0, v[112:113]
	v_cvt_pk_bf16_f32 v96, v115, v104
	v_add_f32_e32 v111, v123, v122
	v_mul_f32_e32 v105, v124, v105
	v_mul_f32_e32 v108, v124, v108
	v_mul_f32_e32 v106, v124, v106
	v_mul_f32_e32 v110, v124, v110
	v_cvt_pk_bf16_f32 v97, v108, v106
	v_cvt_pk_bf16_f32 v98, v110, v116
	v_cvt_pk_bf16_f32 v99, v118, v120
	global_store_dwordx4 v[100:101], v[96:99], off
	v_mul_f32_e32 v109, v124, v109
	v_mul_f32_e32 v107, v124, v107
	v_cvt_pk_bf16_f32 v96, v114, v105
	v_or_b32_e32 v114, 32, v148
	v_mul_f32_e32 v111, v124, v111
	v_cvt_pk_bf16_f32 v97, v109, v107
	v_cvt_pk_bf16_f32 v98, v111, v117
	v_cvt_pk_bf16_f32 v99, v119, v102
	global_store_dwordx4 v[100:101], v[96:99], off offset:64
	v_ashrrev_i32_e32 v115, 31, v114
	v_lshl_add_u64 v[116:117], v[114:115], 2, s[4:5]
	v_lshlrev_b32_e32 v96, 5, v114
	v_and_b32_e32 v136, 0x3fde0, v96
	v_and_b32_e32 v96, 0x1e0, v136
	v_or_b32_e32 v96, v96, v138
	v_and_b32_e32 v136, 0xfffffe1f, v136
	v_lshlrev_b32_e32 v96, 1, v96
	v_lshl_add_u32 v136, v136, 3, v96
	v_add_u32_e32 v136, 0xe500000, v136
	v_lshl_add_u64 v[108:109], v[136:137], 0, s[6:7]
	global_load_dwordx4 v[96:99], v[108:109], off
	global_load_dwordx4 v[100:103], v[108:109], off offset:1024
	global_load_dwordx4 v[104:107], v[108:109], off offset:2048
	s_nop 0
	global_load_dwordx4 v[108:111], v[108:109], off offset:3072
	s_nop 0
	global_load_dword v116, v[116:117], off
	v_mov_b32_e32 v127, v80
	v_mov_b32_e32 v164, v80
	v_mov_b32_e32 v80, v85
	v_mov_b32_e32 v118, v92
	v_mov_b32_e32 v119, v88
	v_mov_b32_e32 v120, v88
	v_mov_b32_e32 v121, v92
	v_mov_b32_e32 v88, v93
	v_mov_b32_e32 v92, v89
	v_mov_b32_e32 v122, v94
	v_mov_b32_e32 v123, v90
	v_mov_b32_e32 v126, v84
	v_mov_b32_e32 v165, v84
	v_mov_b32_e32 v84, v81
	v_mov_b32_e32 v151, v86
	v_mov_b32_e32 v124, v90
	v_mov_b32_e32 v125, v94
	v_mov_b32_e32 v90, v95
	v_mov_b32_e32 v94, v91
	s_waitcnt vmcnt(4)
	v_pk_mul_f32 v[88:89], v[88:89], v[98:99]
	v_pk_mul_f32 v[92:93], v[92:93], v[98:99]
	s_waitcnt vmcnt(2)
	v_pk_mul_f32 v[80:81], v[80:81], v[106:107]
	s_waitcnt vmcnt(1)
	v_mov_b32_e32 v117, v108
	v_pk_mul_f32 v[98:99], v[122:123], v[100:101]
	v_pk_mul_f32 v[84:85], v[84:85], v[106:107]
	s_waitcnt vmcnt(0)
	v_pk_mul_f32 v[106:107], v[150:151], v[116:117]
	v_sub_f32_e32 v80, v80, v81
	v_sub_f32_e32 v88, v88, v89
	v_add_f32_e32 v89, v93, v92
	v_sub_f32_e32 v92, v98, v99
	v_mul_f32_e32 v98, v106, v80
	v_add_f32_e32 v80, v85, v84
	v_pk_mul_f32 v[100:101], v[124:125], v[100:101]
	v_mul_f32_e32 v99, v106, v80
	v_fma_f32 v80, -v82, v109, v107
	v_add_f32_e32 v93, v101, v100
	v_mul_f32_e32 v100, v106, v80
	v_mov_b32_e32 v80, v82
	v_mov_b32_e32 v81, v86
	v_pk_mul_f32 v[80:81], v[80:81], v[108:109]
	v_mov_b32_e32 v82, v87
	v_add_f32_e32 v80, v81, v80
	v_mul_f32_e32 v101, v106, v80
	v_pk_mul_f32 v[80:81], v[82:83], v[110:111]
	v_pk_mul_f32 v[90:91], v[90:91], v[102:103]
	v_pk_mul_f32 v[94:95], v[94:95], v[102:103]
	v_pk_mul_f32 v[102:103], v[126:127], v[104:105]
	v_sub_f32_e32 v80, v80, v81
	v_mov_b32_e32 v86, v83
	v_add_f32_e32 v94, v95, v94
	v_sub_f32_e32 v95, v102, v103
	v_mul_f32_e32 v102, v106, v80
	v_pk_mul_f32 v[80:81], v[86:87], v[110:111]
	v_pk_mul_f32 v[118:119], v[118:119], v[96:97]
	v_add_f32_e32 v80, v81, v80
	v_mul_f32_e32 v86, v106, v80
	v_mad_i64_i32 v[80:81], s[10:11], v114, s47, v[154:155]
	v_pk_mul_f32 v[96:97], v[120:121], v[96:97]
	v_lshl_add_u64 v[80:81], v[80:81], 0, s[28:29]
	v_sub_f32_e32 v115, v118, v119
	v_add_f32_e32 v96, v97, v96
	v_lshl_add_u64 v[80:81], v[80:81], 0, s[8:9]
	v_pk_mul_f32 v[104:105], v[164:165], v[104:105]
	v_sub_f32_e32 v90, v90, v91
	v_mul_f32_e32 v91, v106, v115
	v_mul_f32_e32 v96, v106, v96
	v_mul_f32_e32 v88, v106, v88
	v_lshl_add_u64 v[84:85], v[80:81], 0, v[112:113]
	v_cvt_pk_bf16_f32 v80, v91, v88
	v_mul_f32_e32 v89, v106, v89
	v_mul_f32_e32 v92, v106, v92
	v_mul_f32_e32 v90, v106, v90
	v_mul_f32_e32 v95, v106, v95
	v_add_f32_e32 v97, v105, v104
	v_cvt_pk_bf16_f32 v81, v92, v90
	v_cvt_pk_bf16_f32 v82, v95, v98
	v_cvt_pk_bf16_f32 v83, v100, v102
	global_store_dwordx4 v[84:85], v[80:83], off
	v_mul_f32_e32 v93, v106, v93
	v_mul_f32_e32 v94, v106, v94
	v_cvt_pk_bf16_f32 v80, v96, v89
	v_or_b32_e32 v96, 48, v148
	v_mul_f32_e32 v97, v106, v97
	v_cvt_pk_bf16_f32 v81, v93, v94
	v_cvt_pk_bf16_f32 v82, v97, v99
	v_cvt_pk_bf16_f32 v83, v101, v86
	global_store_dwordx4 v[84:85], v[80:83], off offset:64
	v_ashrrev_i32_e32 v97, 31, v96
	v_lshl_add_u64 v[98:99], v[96:97], 2, s[4:5]
	v_lshlrev_b32_e32 v80, 5, v96
	v_and_b32_e32 v136, 0x3ffe0, v80
	v_and_b32_e32 v80, 0x1e0, v136
	v_or_b32_e32 v80, v80, v138
	v_and_b32_e32 v136, 0xfffffe1f, v136
	v_lshlrev_b32_e32 v80, 1, v80
	v_lshl_add_u32 v136, v136, 3, v80
	v_add_u32_e32 v136, 0xe500000, v136
	v_lshl_add_u64 v[92:93], v[136:137], 0, s[6:7]
	global_load_dwordx4 v[80:83], v[92:93], off
	global_load_dwordx4 v[84:87], v[92:93], off offset:1024
	global_load_dwordx4 v[88:91], v[92:93], off offset:2048
	s_nop 0
	global_load_dwordx4 v[92:95], v[92:93], off offset:3072
	s_nop 0
	global_load_dword v98, v[98:99], off
	v_mov_b32_e32 v109, v64
	v_mov_b32_e32 v110, v64
	v_mov_b32_e32 v64, v69
	v_mov_b32_e32 v100, v76
	v_mov_b32_e32 v101, v72
	v_mov_b32_e32 v102, v72
	v_mov_b32_e32 v103, v76
	v_mov_b32_e32 v72, v77
	v_mov_b32_e32 v76, v73
	v_mov_b32_e32 v104, v78
	v_mov_b32_e32 v105, v74
	v_mov_b32_e32 v108, v68
	v_mov_b32_e32 v111, v68
	v_mov_b32_e32 v68, v65
	v_mov_b32_e32 v151, v70
	v_mov_b32_e32 v106, v74
	v_mov_b32_e32 v107, v78
	v_mov_b32_e32 v74, v79
	v_mov_b32_e32 v78, v75
	s_waitcnt vmcnt(4)
	v_pk_mul_f32 v[72:73], v[72:73], v[82:83]
	v_pk_mul_f32 v[76:77], v[76:77], v[82:83]
	s_waitcnt vmcnt(2)
	v_pk_mul_f32 v[64:65], v[64:65], v[90:91]
	s_waitcnt vmcnt(1)
	v_mov_b32_e32 v99, v92
	v_pk_mul_f32 v[82:83], v[104:105], v[84:85]
	v_pk_mul_f32 v[68:69], v[68:69], v[90:91]
	s_waitcnt vmcnt(0)
	v_pk_mul_f32 v[90:91], v[150:151], v[98:99]
	v_sub_f32_e32 v64, v64, v65
	v_sub_f32_e32 v72, v72, v73
	v_add_f32_e32 v73, v77, v76
	v_sub_f32_e32 v76, v82, v83
	v_mul_f32_e32 v82, v90, v64
	v_add_f32_e32 v64, v69, v68
	v_pk_mul_f32 v[84:85], v[106:107], v[84:85]
	v_mul_f32_e32 v83, v90, v64
	v_fma_f32 v64, -v66, v93, v91
	v_add_f32_e32 v77, v85, v84
	v_mul_f32_e32 v84, v90, v64
	v_mov_b32_e32 v64, v66
	v_mov_b32_e32 v65, v70
	v_pk_mul_f32 v[64:65], v[64:65], v[92:93]
	v_mov_b32_e32 v66, v71
	v_add_f32_e32 v64, v65, v64
	v_mul_f32_e32 v85, v90, v64
	v_pk_mul_f32 v[64:65], v[66:67], v[94:95]
	v_pk_mul_f32 v[74:75], v[74:75], v[86:87]
	v_pk_mul_f32 v[78:79], v[78:79], v[86:87]
	v_pk_mul_f32 v[86:87], v[108:109], v[88:89]
	v_sub_f32_e32 v64, v64, v65
	v_mov_b32_e32 v70, v67
	v_sub_f32_e32 v74, v74, v75
	v_add_f32_e32 v75, v79, v78
	v_sub_f32_e32 v78, v86, v87
	v_mul_f32_e32 v86, v90, v64
	v_pk_mul_f32 v[64:65], v[70:71], v[94:95]
	v_pk_mul_f32 v[100:101], v[100:101], v[80:81]
	v_add_f32_e32 v64, v65, v64
	v_mul_f32_e32 v70, v90, v64
	v_mad_i64_i32 v[64:65], s[10:11], v96, s47, v[154:155]
	v_lshl_add_u64 v[64:65], v[64:65], 0, s[28:29]
	v_pk_mul_f32 v[80:81], v[102:103], v[80:81]
	v_sub_f32_e32 v97, v100, v101
	v_lshl_add_u64 v[64:65], v[64:65], 0, s[8:9]
	v_pk_mul_f32 v[88:89], v[110:111], v[88:89]
	v_add_f32_e32 v80, v81, v80
	v_mul_f32_e32 v81, v90, v97
	v_mul_f32_e32 v72, v90, v72
	v_lshl_add_u64 v[68:69], v[64:65], 0, v[112:113]
	v_cvt_pk_bf16_f32 v64, v81, v72
	v_mul_f32_e32 v80, v90, v80
	v_mul_f32_e32 v73, v90, v73
	v_mul_f32_e32 v76, v90, v76
	v_mul_f32_e32 v74, v90, v74
	v_mul_f32_e32 v78, v90, v78
	v_add_f32_e32 v79, v89, v88
	v_cvt_pk_bf16_f32 v65, v76, v74
	v_cvt_pk_bf16_f32 v66, v78, v82
	v_cvt_pk_bf16_f32 v67, v84, v86
	global_store_dwordx4 v[68:69], v[64:67], off
	v_add_u32_e32 v94, 0x80, v148
	v_mul_f32_e32 v77, v90, v77
	v_cvt_pk_bf16_f32 v64, v80, v73
	v_mul_f32_e32 v75, v90, v75
	v_mul_f32_e32 v79, v90, v79
	v_cvt_pk_bf16_f32 v65, v77, v75
	v_cvt_pk_bf16_f32 v66, v79, v83
	v_cvt_pk_bf16_f32 v67, v85, v70
	global_store_dwordx4 v[68:69], v[64:67], off offset:64
	v_mov_b32_e32 v82, v60
	v_mov_b32_e32 v83, v56
	v_lshlrev_b32_e32 v64, 5, v94
	v_and_b32_e32 v136, 0x3f9e0, v64
	v_and_b32_e32 v64, 0x1e0, v136
	v_or_b32_e32 v64, v64, v138
	v_and_b32_e32 v136, 0xfffffe1f, v136
	v_lshlrev_b32_e32 v64, 1, v64
	v_lshl_add_u32 v136, v136, 3, v64
	v_add_u32_e32 v136, 0xe500000, v136
	v_lshl_add_u64 v[76:77], v[136:137], 0, s[6:7]
	global_load_dwordx4 v[64:67], v[76:77], off
	global_load_dwordx4 v[68:71], v[76:77], off offset:1024
	global_load_dwordx4 v[72:75], v[76:77], off offset:2048
	s_nop 0
	global_load_dwordx4 v[76:79], v[76:77], off offset:3072
	s_nop 0
	global_load_dword v80, v[152:153], off offset:512
	v_mov_b32_e32 v84, v56
	v_mov_b32_e32 v85, v60
	v_mov_b32_e32 v90, v52
	v_mov_b32_e32 v91, v48
	v_mov_b32_e32 v92, v48
	v_mov_b32_e32 v93, v52
	v_mov_b32_e32 v48, v53
	v_mov_b32_e32 v52, v49
	v_mov_b32_e32 v56, v61
	v_mov_b32_e32 v60, v57
	v_mov_b32_e32 v86, v62
	v_mov_b32_e32 v87, v58
	v_mov_b32_e32 v151, v54
	v_mov_b32_e32 v88, v58
	v_mov_b32_e32 v89, v62
	v_mov_b32_e32 v58, v63
	v_mov_b32_e32 v62, v59
	s_waitcnt vmcnt(4)
	v_pk_mul_f32 v[82:83], v[82:83], v[64:65]
	v_pk_mul_f32 v[64:65], v[84:85], v[64:65]
	s_waitcnt vmcnt(2)
	v_pk_mul_f32 v[84:85], v[48:49], v[74:75]
	v_pk_mul_f32 v[48:49], v[52:53], v[74:75]
	s_waitcnt vmcnt(1)
	v_mov_b32_e32 v81, v76
	v_pk_mul_f32 v[56:57], v[56:57], v[66:67]
	v_pk_mul_f32 v[60:61], v[60:61], v[66:67]
	v_pk_mul_f32 v[66:67], v[86:87], v[68:69]
	s_waitcnt vmcnt(0)
	v_pk_mul_f32 v[52:53], v[150:151], v[80:81]
	v_add_f32_e32 v48, v49, v48
	v_sub_f32_e32 v56, v56, v57
	v_add_f32_e32 v57, v61, v60
	v_sub_f32_e32 v60, v66, v67
	v_mul_f32_e32 v66, v52, v48
	v_fma_f32 v48, -v50, v77, v53
	v_mul_f32_e32 v67, v52, v48
	v_mov_b32_e32 v48, v50
	v_mov_b32_e32 v49, v54
	v_pk_mul_f32 v[48:49], v[48:49], v[76:77]
	v_pk_mul_f32 v[68:69], v[88:89], v[68:69]
	v_add_f32_e32 v48, v49, v48
	v_mov_b32_e32 v50, v55
	v_add_f32_e32 v61, v69, v68
	v_mul_f32_e32 v68, v52, v48
	v_pk_mul_f32 v[48:49], v[50:51], v[78:79]
	v_mov_b32_e32 v54, v51
	v_sub_f32_e32 v48, v48, v49
	v_mul_f32_e32 v69, v52, v48
	v_pk_mul_f32 v[48:49], v[54:55], v[78:79]
	v_pk_mul_f32 v[58:59], v[58:59], v[70:71]
	v_add_f32_e32 v48, v49, v48
	v_mul_f32_e32 v54, v52, v48
	v_mad_i64_i32 v[48:49], s[10:11], v94, s47, v[154:155]
	v_pk_mul_f32 v[62:63], v[62:63], v[70:71]
	v_pk_mul_f32 v[70:71], v[90:91], v[72:73]
	v_pk_mul_f32 v[72:73], v[92:93], v[72:73]
	v_lshl_add_u64 v[48:49], v[48:49], 0, s[28:29]
	v_sub_f32_e32 v74, v82, v83
	v_add_f32_e32 v64, v65, v64
	v_sub_f32_e32 v58, v58, v59
	v_add_f32_e32 v59, v63, v62
	v_sub_f32_e32 v62, v70, v71
	v_add_f32_e32 v63, v73, v72
	v_sub_f32_e32 v65, v84, v85
	v_lshl_add_u64 v[48:49], v[48:49], 0, s[8:9]
	v_mul_f32_e32 v74, v52, v74
	v_mul_f32_e32 v64, v52, v64
	v_mul_f32_e32 v56, v52, v56
	v_mul_f32_e32 v57, v52, v57
	v_mul_f32_e32 v60, v52, v60
	v_mul_f32_e32 v61, v52, v61
	v_mul_f32_e32 v58, v52, v58
	v_mul_f32_e32 v59, v52, v59
	v_mul_f32_e32 v62, v52, v62
	v_mul_f32_e32 v63, v52, v63
	v_mul_f32_e32 v65, v52, v65
	v_lshl_add_u64 v[52:53], v[48:49], 0, v[112:113]
	v_cvt_pk_bf16_f32 v48, v74, v56
	v_cvt_pk_bf16_f32 v49, v60, v58
	v_cvt_pk_bf16_f32 v50, v62, v65
	v_cvt_pk_bf16_f32 v51, v67, v69
	global_store_dwordx4 v[52:53], v[48:51], off
	v_add_u32_e32 v74, 0x90, v148
	v_mov_b32_e32 v67, v40
	v_cvt_pk_bf16_f32 v48, v64, v57
	v_cvt_pk_bf16_f32 v49, v61, v59
	v_cvt_pk_bf16_f32 v50, v63, v66
	v_cvt_pk_bf16_f32 v51, v68, v54
	global_store_dwordx4 v[52:53], v[48:51], off offset:64
	v_mov_b32_e32 v66, v44
	v_mov_b32_e32 v68, v40
	v_lshlrev_b32_e32 v48, 5, v74
	v_and_b32_e32 v136, 0x3fbe0, v48
	v_and_b32_e32 v48, 0x1e0, v136
	v_or_b32_e32 v48, v48, v138
	v_and_b32_e32 v136, 0xfffffe1f, v136
	v_lshlrev_b32_e32 v48, 1, v48
	v_lshl_add_u32 v136, v136, 3, v48
	v_add_u32_e32 v136, 0xe500000, v136
	v_lshl_add_u64 v[60:61], v[136:137], 0, s[6:7]
	global_load_dwordx4 v[48:51], v[60:61], off
	global_load_dwordx4 v[52:55], v[60:61], off offset:1024
	global_load_dwordx4 v[56:59], v[60:61], off offset:2048
	s_nop 0
	global_load_dwordx4 v[60:63], v[60:61], off offset:3072
	s_nop 0
	global_load_dword v64, v[152:153], off offset:576
	v_mov_b32_e32 v69, v44
	v_mov_b32_e32 v70, v46
	v_mov_b32_e32 v71, v42
	v_mov_b32_e32 v72, v42
	v_mov_b32_e32 v73, v46
	v_mov_b32_e32 v42, v47
	v_mov_b32_e32 v46, v43
	v_mov_b32_e32 v40, v45
	v_mov_b32_e32 v44, v41
	v_mov_b32_e32 v151, v38
	s_waitcnt vmcnt(4)
	v_pk_mul_f32 v[66:67], v[66:67], v[48:49]
	v_pk_mul_f32 v[48:49], v[68:69], v[48:49]
	s_waitcnt vmcnt(3)
	v_pk_mul_f32 v[42:43], v[42:43], v[54:55]
	v_pk_mul_f32 v[46:47], v[46:47], v[54:55]
	v_mov_b32_e32 v54, v36
	v_mov_b32_e32 v55, v32
	v_mov_b32_e32 v68, v32
	v_mov_b32_e32 v69, v36
	v_mov_b32_e32 v32, v37
	v_mov_b32_e32 v36, v33
	s_waitcnt vmcnt(2)
	v_pk_mul_f32 v[54:55], v[54:55], v[56:57]
	v_pk_mul_f32 v[56:57], v[68:69], v[56:57]
	v_pk_mul_f32 v[68:69], v[32:33], v[58:59]
	v_pk_mul_f32 v[32:33], v[36:37], v[58:59]
	s_waitcnt vmcnt(1)
	v_mov_b32_e32 v65, v60
	v_pk_mul_f32 v[40:41], v[40:41], v[50:51]
	v_pk_mul_f32 v[44:45], v[44:45], v[50:51]
	v_pk_mul_f32 v[50:51], v[70:71], v[52:53]
	s_waitcnt vmcnt(0)
	v_pk_mul_f32 v[36:37], v[150:151], v[64:65]
	v_add_f32_e32 v32, v33, v32
	v_sub_f32_e32 v40, v40, v41
	v_add_f32_e32 v41, v45, v44
	v_sub_f32_e32 v44, v50, v51
	v_mul_f32_e32 v50, v36, v32
	v_fma_f32 v32, -v34, v61, v37
	v_mul_f32_e32 v51, v36, v32
	v_mov_b32_e32 v32, v34
	v_mov_b32_e32 v33, v38
	v_pk_mul_f32 v[32:33], v[32:33], v[60:61]
	v_pk_mul_f32 v[52:53], v[72:73], v[52:53]
	v_add_f32_e32 v32, v33, v32
	v_mov_b32_e32 v34, v39
	v_add_f32_e32 v45, v53, v52
	v_mul_f32_e32 v52, v36, v32
	v_pk_mul_f32 v[32:33], v[34:35], v[62:63]
	v_mov_b32_e32 v38, v35
	v_sub_f32_e32 v32, v32, v33
	v_mul_f32_e32 v53, v36, v32
	v_pk_mul_f32 v[32:33], v[38:39], v[62:63]
	v_sub_f32_e32 v58, v66, v67
	v_add_f32_e32 v32, v33, v32
	v_mul_f32_e32 v38, v36, v32
	v_mad_i64_i32 v[32:33], s[10:11], v74, s47, v[154:155]
	v_lshl_add_u64 v[32:33], v[32:33], 0, s[28:29]
	v_add_f32_e32 v48, v49, v48
	v_sub_f32_e32 v42, v42, v43
	v_add_f32_e32 v43, v47, v46
	v_sub_f32_e32 v46, v54, v55
	v_add_f32_e32 v47, v57, v56
	v_sub_f32_e32 v49, v68, v69
	v_lshl_add_u64 v[32:33], v[32:33], 0, s[8:9]
	v_mul_f32_e32 v58, v36, v58
	v_mul_f32_e32 v48, v36, v48
	v_mul_f32_e32 v40, v36, v40
	v_mul_f32_e32 v41, v36, v41
	v_mul_f32_e32 v44, v36, v44
	v_mul_f32_e32 v45, v36, v45
	v_mul_f32_e32 v42, v36, v42
	v_mul_f32_e32 v43, v36, v43
	v_mul_f32_e32 v46, v36, v46
	v_mul_f32_e32 v47, v36, v47
	v_mul_f32_e32 v49, v36, v49
	v_lshl_add_u64 v[36:37], v[32:33], 0, v[112:113]
	v_cvt_pk_bf16_f32 v32, v58, v40
	v_cvt_pk_bf16_f32 v33, v44, v42
	v_cvt_pk_bf16_f32 v34, v46, v49
	v_cvt_pk_bf16_f32 v35, v51, v53
	global_store_dwordx4 v[36:37], v[32:35], off
	v_add_u32_e32 v56, 0xa0, v148
	v_mov_b32_e32 v51, v24
	v_cvt_pk_bf16_f32 v32, v48, v41
	v_cvt_pk_bf16_f32 v33, v45, v43
	v_cvt_pk_bf16_f32 v34, v47, v50
	v_cvt_pk_bf16_f32 v35, v52, v38
	global_store_dwordx4 v[36:37], v[32:35], off offset:64
	v_mov_b32_e32 v50, v28
	v_mov_b32_e32 v52, v24
	v_lshlrev_b32_e32 v32, 5, v56
	v_and_b32_e32 v136, 0x3fde0, v32
	v_and_b32_e32 v32, 0x1e0, v136
	v_or_b32_e32 v32, v32, v138
	v_and_b32_e32 v136, 0xfffffe1f, v136
	v_lshlrev_b32_e32 v32, 1, v32
	v_lshl_add_u32 v136, v136, 3, v32
	v_add_u32_e32 v136, 0xe500000, v136
	v_lshl_add_u64 v[44:45], v[136:137], 0, s[6:7]
	global_load_dwordx4 v[32:35], v[44:45], off
	global_load_dwordx4 v[36:39], v[44:45], off offset:1024
	global_load_dwordx4 v[40:43], v[44:45], off offset:2048
	s_nop 0
	global_load_dwordx4 v[44:47], v[44:45], off offset:3072
	s_nop 0
	global_load_dword v48, v[152:153], off offset:640
	v_mov_b32_e32 v53, v28
	v_mov_b32_e32 v24, v29
	v_mov_b32_e32 v28, v25
	v_mov_b32_e32 v54, v30
	v_mov_b32_e32 v55, v26
	v_mov_b32_e32 v151, v22
	s_waitcnt vmcnt(4)
	v_pk_mul_f32 v[50:51], v[50:51], v[32:33]
	v_pk_mul_f32 v[32:33], v[52:53], v[32:33]
	v_mov_b32_e32 v52, v26
	v_mov_b32_e32 v53, v30
	v_mov_b32_e32 v26, v31
	v_mov_b32_e32 v30, v27
	v_pk_mul_f32 v[24:25], v[24:25], v[34:35]
	v_pk_mul_f32 v[28:29], v[28:29], v[34:35]
	s_waitcnt vmcnt(3)
	v_pk_mul_f32 v[34:35], v[54:55], v[36:37]
	v_pk_mul_f32 v[36:37], v[52:53], v[36:37]
	v_pk_mul_f32 v[52:53], v[26:27], v[38:39]
	v_pk_mul_f32 v[26:27], v[30:31], v[38:39]
	v_mov_b32_e32 v30, v20
	v_mov_b32_e32 v31, v16
	v_mov_b32_e32 v38, v16
	v_mov_b32_e32 v39, v20
	v_mov_b32_e32 v16, v21
	v_mov_b32_e32 v20, v17
	s_waitcnt vmcnt(2)
	v_pk_mul_f32 v[30:31], v[30:31], v[40:41]
	v_pk_mul_f32 v[38:39], v[38:39], v[40:41]
	v_pk_mul_f32 v[40:41], v[16:17], v[42:43]
	v_pk_mul_f32 v[16:17], v[20:21], v[42:43]
	s_waitcnt vmcnt(1)
	v_mov_b32_e32 v49, v44
	s_waitcnt vmcnt(0)
	v_pk_mul_f32 v[20:21], v[150:151], v[48:49]
	v_add_f32_e32 v16, v17, v16
	v_sub_f32_e32 v24, v24, v25
	v_add_f32_e32 v25, v29, v28
	v_sub_f32_e32 v28, v34, v35
	v_mul_f32_e32 v34, v20, v16
	v_fma_f32 v16, -v18, v45, v21
	v_mul_f32_e32 v35, v20, v16
	v_mov_b32_e32 v16, v18
	v_mov_b32_e32 v17, v22
	v_pk_mul_f32 v[16:17], v[16:17], v[44:45]
	v_mov_b32_e32 v18, v23
	v_add_f32_e32 v16, v17, v16
	v_add_f32_e32 v29, v37, v36
	v_mul_f32_e32 v36, v20, v16
	v_pk_mul_f32 v[16:17], v[18:19], v[46:47]
	v_mov_b32_e32 v22, v19
	v_sub_f32_e32 v16, v16, v17
	v_mul_f32_e32 v37, v20, v16
	v_pk_mul_f32 v[16:17], v[22:23], v[46:47]
	v_sub_f32_e32 v42, v50, v51
	v_add_f32_e32 v16, v17, v16
	v_mul_f32_e32 v22, v20, v16
	v_mad_i64_i32 v[16:17], s[10:11], v56, s47, v[154:155]
	v_lshl_add_u64 v[16:17], v[16:17], 0, s[28:29]
	v_add_f32_e32 v32, v33, v32
	v_sub_f32_e32 v33, v52, v53
	v_add_f32_e32 v26, v27, v26
	v_sub_f32_e32 v27, v30, v31
	v_add_f32_e32 v30, v39, v38
	v_sub_f32_e32 v31, v40, v41
	v_lshl_add_u64 v[16:17], v[16:17], 0, s[8:9]
	v_mul_f32_e32 v42, v20, v42
	v_mul_f32_e32 v32, v20, v32
	v_mul_f32_e32 v24, v20, v24
	v_mul_f32_e32 v25, v20, v25
	v_mul_f32_e32 v28, v20, v28
	v_mul_f32_e32 v29, v20, v29
	v_mul_f32_e32 v33, v20, v33
	v_mul_f32_e32 v26, v20, v26
	v_mul_f32_e32 v27, v20, v27
	v_mul_f32_e32 v30, v20, v30
	v_mul_f32_e32 v31, v20, v31
	v_lshl_add_u64 v[20:21], v[16:17], 0, v[112:113]
	v_cvt_pk_bf16_f32 v16, v42, v24
	v_cvt_pk_bf16_f32 v17, v28, v33
	v_cvt_pk_bf16_f32 v18, v27, v31
	v_cvt_pk_bf16_f32 v19, v35, v37
	global_store_dwordx4 v[20:21], v[16:19], off
	v_add_u32_e32 v38, 0xb0, v148
	v_mov_b32_e32 v35, v8
	v_cvt_pk_bf16_f32 v16, v32, v25
	v_cvt_pk_bf16_f32 v17, v29, v26
	v_cvt_pk_bf16_f32 v18, v30, v34
	v_cvt_pk_bf16_f32 v19, v36, v22
	global_store_dwordx4 v[20:21], v[16:19], off offset:64
	v_mov_b32_e32 v34, v12
	v_mov_b32_e32 v36, v8
	v_lshlrev_b32_e32 v16, 5, v38
	v_and_b32_e32 v136, 0x3ffe0, v16
	v_and_b32_e32 v16, 0x1e0, v136
	v_or_b32_e32 v16, v16, v138
	v_and_b32_e32 v136, 0xfffffe1f, v136
	v_lshlrev_b32_e32 v16, 1, v16
	v_lshl_add_u32 v136, v136, 3, v16
	v_add_u32_e32 v136, 0xe500000, v136
	v_lshl_add_u64 v[28:29], v[136:137], 0, s[6:7]
	global_load_dwordx4 v[16:19], v[28:29], off
	global_load_dwordx4 v[20:23], v[28:29], off offset:1024
	global_load_dwordx4 v[24:27], v[28:29], off offset:2048
	s_nop 0
	global_load_dwordx4 v[28:31], v[28:29], off offset:3072
	s_nop 0
	global_load_dword v32, v[152:153], off offset:704
	v_mov_b32_e32 v37, v12
	v_mov_b32_e32 v8, v13
	v_mov_b32_e32 v12, v9
	v_mov_b32_e32 v151, v6
	s_waitcnt vmcnt(4)
	v_pk_mul_f32 v[34:35], v[34:35], v[16:17]
	v_pk_mul_f32 v[16:17], v[36:37], v[16:17]
	v_pk_mul_f32 v[36:37], v[8:9], v[18:19]
	v_pk_mul_f32 v[8:9], v[12:13], v[18:19]
	v_mov_b32_e32 v12, v14
	v_mov_b32_e32 v13, v10
	v_mov_b32_e32 v18, v10
	v_mov_b32_e32 v19, v14
	v_mov_b32_e32 v10, v15
	v_mov_b32_e32 v14, v11
	s_waitcnt vmcnt(3)
	v_pk_mul_f32 v[12:13], v[12:13], v[20:21]
	v_pk_mul_f32 v[18:19], v[18:19], v[20:21]
	v_pk_mul_f32 v[20:21], v[10:11], v[22:23]
	v_pk_mul_f32 v[10:11], v[14:15], v[22:23]
	v_mov_b32_e32 v14, v4
	v_mov_b32_e32 v15, v0
	v_mov_b32_e32 v22, v0
	v_mov_b32_e32 v23, v4
	v_mov_b32_e32 v0, v5
	v_mov_b32_e32 v4, v1
	s_waitcnt vmcnt(2)
	v_pk_mul_f32 v[14:15], v[14:15], v[24:25]
	v_pk_mul_f32 v[22:23], v[22:23], v[24:25]
	v_pk_mul_f32 v[24:25], v[0:1], v[26:27]
	v_pk_mul_f32 v[0:1], v[4:5], v[26:27]
	s_waitcnt vmcnt(1)
	v_mov_b32_e32 v33, v28
	s_waitcnt vmcnt(0)
	v_pk_mul_f32 v[4:5], v[150:151], v[32:33]
	v_add_f32_e32 v0, v1, v0
	v_add_f32_e32 v8, v9, v8
	v_sub_f32_e32 v9, v12, v13
	v_add_f32_e32 v12, v19, v18
	v_mul_f32_e32 v18, v4, v0
	v_fma_f32 v0, -v2, v29, v5
	v_mul_f32_e32 v19, v4, v0
	v_mov_b32_e32 v0, v2
	v_mov_b32_e32 v1, v6
	v_pk_mul_f32 v[0:1], v[0:1], v[28:29]
	v_mov_b32_e32 v2, v7
	v_add_f32_e32 v0, v1, v0
	v_sub_f32_e32 v13, v20, v21
	v_mul_f32_e32 v20, v4, v0
	v_pk_mul_f32 v[0:1], v[2:3], v[30:31]
	v_mov_b32_e32 v6, v3
	v_sub_f32_e32 v0, v0, v1
	v_mul_f32_e32 v21, v4, v0
	v_pk_mul_f32 v[0:1], v[6:7], v[30:31]
	v_sub_f32_e32 v26, v34, v35
	v_add_f32_e32 v0, v1, v0
	v_mul_f32_e32 v6, v4, v0
	v_mad_i64_i32 v[0:1], s[10:11], v38, s47, v[154:155]
	v_lshl_add_u64 v[0:1], v[0:1], 0, s[28:29]
	v_add_f32_e32 v16, v17, v16
	v_sub_f32_e32 v17, v36, v37
	v_add_f32_e32 v10, v11, v10
	v_sub_f32_e32 v11, v14, v15
	v_add_f32_e32 v14, v23, v22
	v_sub_f32_e32 v15, v24, v25
	v_lshl_add_u64 v[0:1], v[0:1], 0, s[8:9]
	v_mul_f32_e32 v26, v4, v26
	v_mul_f32_e32 v16, v4, v16
	v_mul_f32_e32 v17, v4, v17
	v_mul_f32_e32 v8, v4, v8
	v_mul_f32_e32 v9, v4, v9
	v_mul_f32_e32 v12, v4, v12
	v_mul_f32_e32 v13, v4, v13
	v_mul_f32_e32 v10, v4, v10
	v_mul_f32_e32 v11, v4, v11
	v_mul_f32_e32 v14, v4, v14
	v_mul_f32_e32 v15, v4, v15
	v_lshl_add_u64 v[4:5], v[0:1], 0, v[112:113]
	v_cvt_pk_bf16_f32 v0, v26, v17
	v_cvt_pk_bf16_f32 v1, v9, v13
	v_cvt_pk_bf16_f32 v2, v11, v15
	v_cvt_pk_bf16_f32 v3, v19, v21
	global_store_dwordx4 v[4:5], v[0:3], off
	s_nop 1
	v_cvt_pk_bf16_f32 v0, v16, v8
	v_cvt_pk_bf16_f32 v1, v12, v10
	v_cvt_pk_bf16_f32 v2, v14, v18
	v_cvt_pk_bf16_f32 v3, v20, v6
	global_store_dwordx4 v[4:5], v[0:3], off offset:64
	s_andn2_b64 vcc, exec, s[0:1]
	s_mov_b64 s[0:1], -1
	s_cbranch_vccnz .LBB0_286
